# grid barriers 3-9: L2 write-back issued once per XCC by its last arriving workgroup (per-XCC arrival counters by HW_REG_XCC_ID, census-checked with flat fallback) instead of once per workgroup
# speedup vs baseline: 1.0149x; 1.0149x over previous
; __global__ void __launch_bounds__(NTH, 2) mega_kernel(Params p) {
;     ...
;   phase0a(p, smem);
;   wait_mod(p);
;   phase1(p);
;   phase0b(p, smem);
;   grid.sync();
.LBB0_188:
	v_lshrrev_b32_e32 v1, 20, v0
	v_lshrrev_b32_e32 v0, 10, v0
	v_or_b32_e32 v0, v0, v1
	s_movk_i32 s4, 0x3ff
	v_and_or_b32 v0, v0, s4, v220
	v_cmp_eq_u32_e64 s[72:73], 0, v0
	s_waitcnt vmcnt(0) lgkmcnt(0)
	s_barrier
	s_and_saveexec_b64 s[4:5], s[72:73]
	s_cbranch_execz .LBB0_198
	buffer_wbl2 sc1
	s_load_dwordx2 s[6:7], s[0:1], 0x158
	s_load_dword s8, s[0:1], 0x490
	s_getreg_b32 s9, hwreg(HW_REG_XCC_ID, 0, 4)
	v_mov_b32_e32 v0, 0
	v_mov_b32_e32 v1, 1
	s_lshl_b32 s9, s9, 2
	v_mov_b32_e32 v3, s9
	s_waitcnt lgkmcnt(0)
	global_atomic_add v3, v1, s[6:7] offset:192
	s_waitcnt vmcnt(0)
	global_atomic_add v0, v1, s[6:7] offset:128
	s_mul_i32 s8, s8, 1

; #define RUNPH(k, call) for (int rep_ = 0; rep_ < (((REPMASK) >> (k)) & 1) + 1; ++rep_) { call; grid.sync(); }
; __global__ void __launch_bounds__(NTH, 2) mega_kernel(Params p) {
;     ...
;   RUNPH(2, phase2(p, smem))
.LBB0_302:
	s_waitcnt vmcnt(0) lgkmcnt(0)
	s_barrier
	s_and_saveexec_b64 s[4:5], s[72:73]
	s_cbranch_execz .LBB0_312
	buffer_wbl2 sc1
	s_load_dwordx2 s[6:7], s[0:1], 0x158
	s_load_dword s8, s[0:1], 0x490
	s_getreg_b32 s9, hwreg(HW_REG_XCC_ID, 0, 4)
	v_mov_b32_e32 v0, 0
	v_mov_b32_e32 v1, 1
	s_lshl_b32 s9, s9, 2
	v_mov_b32_e32 v3, s9
	s_waitcnt lgkmcnt(0)
	global_load_dword v2, v3, s[6:7] offset:192 sc1
	s_lshr_b32 s10, s8, 3
	s_waitcnt vmcnt(0)
	v_cmp_eq_u32_e32 vcc, s10, v2
	s_cbranch_vccnz .Lgs2_cok
	global_atomic_add v0, v1, s[6:7] offset:140
	s_waitcnt vmcnt(0)
.Lgs2_cok:
	global_atomic_add v0, v1, s[6:7] offset:128
	s_mul_i32 s8, s8, 2

; #define RUNPH(k, call) for (int rep_ = 0; rep_ < (((REPMASK) >> (k)) & 1) + 1; ++rep_) { call; grid.sync(); }
; __global__ void __launch_bounds__(NTH, 2) mega_kernel(Params p) {
;     ...
;   RUNPH(3, phase3(p, smem))
.LBB0_525:
	s_waitcnt vmcnt(0) lgkmcnt(0)
	s_barrier
	s_and_saveexec_b64 s[4:5], s[72:73]
	s_cbranch_execz .LBB0_535
	s_load_dwordx2 s[6:7], s[0:1], 0x158
	s_load_dword s8, s[0:1], 0x490
	s_getreg_b32 s9, hwreg(HW_REG_XCC_ID, 0, 4)
	v_mov_b32_e32 v0, 0
	v_mov_b32_e32 v1, 1
	s_lshl_b32 s9, s9, 2
	v_mov_b32_e32 v3, s9
	s_waitcnt lgkmcnt(0)
	global_atomic_add v2, v3, v1, s[6:7] offset:160 sc0
	global_load_dword v3, v0, s[6:7] offset:140 sc1
	s_lshr_b32 s10, s8, 3
	s_mul_i32 s10, s10, 1
	s_waitcnt vmcnt(0)
	v_cmp_ne_u32_e32 vcc, 0, v3
	s_cbranch_vccnz .Lgs3_flat
	v_add_u32_e32 v2, 1, v2
	v_cmp_ne_u32_e32 vcc, s10, v2
	s_cbranch_vccnz .Lgs3_wait
	buffer_wbl2 sc1
	s_waitcnt vmcnt(0)
	global_atomic_add v0, v1, s[6:7] offset:136
.Lgs3_wait:
	s_movk_i32 s10, 8
	s_movk_i32 s11, 0x4000
.Lgs3_poll:
	global_load_dword v2, v0, s[6:7] offset:136 sc1
	s_waitcnt vmcnt(0)
	v_cmp_gt_u32_e32 vcc, s10, v2
	s_cbranch_vccz .Lgs3_done
	s_sleep 8
	s_sub_u32 s11, s11, 1
	s_cmp_lg_u32 s11, 0
	s_cbranch_scc1 .Lgs3_poll
	s_branch .Lgs3_done
.Lgs3_flat:
	buffer_wbl2 sc1
	s_waitcnt vmcnt(0)
	global_atomic_add v0, v1, s[6:7] offset:128
	s_mul_i32 s8, s8, 3

; #define RUNPH(k, call) for (int rep_ = 0; rep_ < (((REPMASK) >> (k)) & 1) + 1; ++rep_) { call; grid.sync(); }
; __global__ void __launch_bounds__(NTH, 2) mega_kernel(Params p) {
;     ...
;   RUNPH(4, phase4(p, smem))
.LBB0_645:
	s_waitcnt vmcnt(0) lgkmcnt(0)
	s_barrier
	s_and_saveexec_b64 s[4:5], s[72:73]
	s_cbranch_execz .LBB0_655
	s_load_dwordx2 s[6:7], s[0:1], 0x158
	s_load_dword s8, s[0:1], 0x490
	s_getreg_b32 s9, hwreg(HW_REG_XCC_ID, 0, 4)
	v_mov_b32_e32 v0, 0
	v_mov_b32_e32 v1, 1
	s_lshl_b32 s9, s9, 2
	v_mov_b32_e32 v3, s9
	s_waitcnt lgkmcnt(0)
	global_atomic_add v2, v3, v1, s[6:7] offset:160 sc0
	global_load_dword v3, v0, s[6:7] offset:140 sc1
	s_lshr_b32 s10, s8, 3
	s_mul_i32 s10, s10, 2
	s_waitcnt vmcnt(0)
	v_cmp_ne_u32_e32 vcc, 0, v3
	s_cbranch_vccnz .Lgs4_flat
	v_add_u32_e32 v2, 1, v2
	v_cmp_ne_u32_e32 vcc, s10, v2
	s_cbranch_vccnz .Lgs4_wait
	buffer_wbl2 sc1
	s_waitcnt vmcnt(0)
	global_atomic_add v0, v1, s[6:7] offset:136
.Lgs4_wait:
	s_movk_i32 s10, 16
	s_movk_i32 s11, 0x4000

; #define RUNPH(k, call) for (int rep_ = 0; rep_ < (((REPMASK) >> (k)) & 1) + 1; ++rep_) { call; grid.sync(); }
; __global__ void __launch_bounds__(NTH, 2) mega_kernel(Params p) {
;     ...
;   RUNPH(4, phase4(p, smem))
.Lgs4_flat:
	buffer_wbl2 sc1
	s_waitcnt vmcnt(0)
	global_atomic_add v0, v1, s[6:7] offset:128
	s_mul_i32 s8, s8, 4

; #define RUNPH(k, call) for (int rep_ = 0; rep_ < (((REPMASK) >> (k)) & 1) + 1; ++rep_) { call; grid.sync(); }
; __global__ void __launch_bounds__(NTH, 2) mega_kernel(Params p) {
;     ...
;   RUNPH(5, phase5(p, smem))
.LBB0_882:
	s_waitcnt vmcnt(0) lgkmcnt(0)
	s_barrier
	s_and_saveexec_b64 s[4:5], s[72:73]
	s_cbranch_execz .LBB0_892
	s_load_dwordx2 s[6:7], s[0:1], 0x158
	s_load_dword s8, s[0:1], 0x490
	s_getreg_b32 s9, hwreg(HW_REG_XCC_ID, 0, 4)
	v_mov_b32_e32 v0, 0
	v_mov_b32_e32 v1, 1
	s_lshl_b32 s9, s9, 2
	v_mov_b32_e32 v3, s9
	s_waitcnt lgkmcnt(0)
	global_atomic_add v2, v3, v1, s[6:7] offset:160 sc0
	global_load_dword v3, v0, s[6:7] offset:140 sc1
	s_lshr_b32 s10, s8, 3
	s_mul_i32 s10, s10, 3
	s_waitcnt vmcnt(0)
	v_cmp_ne_u32_e32 vcc, 0, v3
	s_cbranch_vccnz .Lgs5_flat
	v_add_u32_e32 v2, 1, v2
	v_cmp_ne_u32_e32 vcc, s10, v2
	s_cbranch_vccnz .Lgs5_wait
	buffer_wbl2 sc1
	s_waitcnt vmcnt(0)
	global_atomic_add v0, v1, s[6:7] offset:136
.Lgs5_wait:
	s_movk_i32 s10, 24
	s_movk_i32 s11, 0x4000

; #define RUNPH(k, call) for (int rep_ = 0; rep_ < (((REPMASK) >> (k)) & 1) + 1; ++rep_) { call; grid.sync(); }
; __global__ void __launch_bounds__(NTH, 2) mega_kernel(Params p) {
;     ...
;   RUNPH(5, phase5(p, smem))
.Lgs5_flat:
	buffer_wbl2 sc1
	s_waitcnt vmcnt(0)
	global_atomic_add v0, v1, s[6:7] offset:128
	s_mul_i32 s8, s8, 5

; #define RUNPH(k, call) for (int rep_ = 0; rep_ < (((REPMASK) >> (k)) & 1) + 1; ++rep_) { call; grid.sync(); }
; __global__ void __launch_bounds__(NTH, 2) mega_kernel(Params p) {
;     ...
;   RUNPH(6, phase6(p, smem))
.LBB0_929:
	s_waitcnt vmcnt(0) lgkmcnt(0)
	s_barrier
	s_and_saveexec_b64 s[4:5], s[72:73]
	s_cbranch_execz .LBB0_939
	s_load_dwordx2 s[6:7], s[0:1], 0x158
	s_load_dword s8, s[0:1], 0x490
	s_getreg_b32 s9, hwreg(HW_REG_XCC_ID, 0, 4)
	v_mov_b32_e32 v0, 0
	v_mov_b32_e32 v1, 1
	s_lshl_b32 s9, s9, 2
	v_mov_b32_e32 v3, s9
	s_waitcnt lgkmcnt(0)
	global_atomic_add v2, v3, v1, s[6:7] offset:160 sc0
	global_load_dword v3, v0, s[6:7] offset:140 sc1
	s_lshr_b32 s10, s8, 3
	s_mul_i32 s10, s10, 4
	s_waitcnt vmcnt(0)
	v_cmp_ne_u32_e32 vcc, 0, v3
	s_cbranch_vccnz .Lgs6_flat
	v_add_u32_e32 v2, 1, v2
	v_cmp_ne_u32_e32 vcc, s10, v2
	s_cbranch_vccnz .Lgs6_wait
	buffer_wbl2 sc1
	s_waitcnt vmcnt(0)
	global_atomic_add v0, v1, s[6:7] offset:136
.Lgs6_wait:
	s_movk_i32 s10, 32
	s_movk_i32 s11, 0x4000

; #define RUNPH(k, call) for (int rep_ = 0; rep_ < (((REPMASK) >> (k)) & 1) + 1; ++rep_) { call; grid.sync(); }
; __global__ void __launch_bounds__(NTH, 2) mega_kernel(Params p) {
;     ...
;   RUNPH(6, phase6(p, smem))
.Lgs6_flat:
	buffer_wbl2 sc1
	s_waitcnt vmcnt(0)
	global_atomic_add v0, v1, s[6:7] offset:128
	s_mul_i32 s8, s8, 6

; #define RUNPH(k, call) for (int rep_ = 0; rep_ < (((REPMASK) >> (k)) & 1) + 1; ++rep_) { call; grid.sync(); }
; __global__ void __launch_bounds__(NTH, 2) mega_kernel(Params p) {
;     ...
;   RUNPH(7, phase7(p, smem))
.LBB0_968:
	s_or_b64 exec, exec, s[18:19]
	s_waitcnt vmcnt(0) lgkmcnt(0)
	s_barrier
	s_and_saveexec_b64 s[4:5], s[72:73]
	s_cbranch_execz .LBB0_978
	s_load_dwordx2 s[6:7], s[0:1], 0x158
	s_load_dword s8, s[0:1], 0x490
	s_getreg_b32 s9, hwreg(HW_REG_XCC_ID, 0, 4)
	v_mov_b32_e32 v0, 0
	v_mov_b32_e32 v1, 1
	s_lshl_b32 s9, s9, 2
	v_mov_b32_e32 v3, s9
	s_waitcnt lgkmcnt(0)
	global_atomic_add v2, v3, v1, s[6:7] offset:160 sc0
	global_load_dword v3, v0, s[6:7] offset:140 sc1
	s_lshr_b32 s10, s8, 3
	s_mul_i32 s10, s10, 5
	s_waitcnt vmcnt(0)
	v_cmp_ne_u32_e32 vcc, 0, v3
	s_cbranch_vccnz .Lgs7_flat
	v_add_u32_e32 v2, 1, v2
	v_cmp_ne_u32_e32 vcc, s10, v2
	s_cbranch_vccnz .Lgs7_wait
	buffer_wbl2 sc1
	s_waitcnt vmcnt(0)
	global_atomic_add v0, v1, s[6:7] offset:136
.Lgs7_wait:
	s_movk_i32 s10, 40
	s_movk_i32 s11, 0x4000

; #define RUNPH(k, call) for (int rep_ = 0; rep_ < (((REPMASK) >> (k)) & 1) + 1; ++rep_) { call; grid.sync(); }
; __global__ void __launch_bounds__(NTH, 2) mega_kernel(Params p) {
;     ...
;   RUNPH(7, phase7(p, smem))
.Lgs7_flat:
	buffer_wbl2 sc1
	s_waitcnt vmcnt(0)
	global_atomic_add v0, v1, s[6:7] offset:128
	s_mul_i32 s8, s8, 7

; #define RUNPH(k, call) for (int rep_ = 0; rep_ < (((REPMASK) >> (k)) & 1) + 1; ++rep_) { call; grid.sync(); }
; __global__ void __launch_bounds__(NTH, 2) mega_kernel(Params p) {
;     ...
;   RUNPH(8, phase8(p))
.LBB0_1175:
	s_or_b64 exec, exec, s[88:89]
	s_waitcnt vmcnt(0) lgkmcnt(0)
	s_barrier
	s_and_saveexec_b64 s[4:5], s[72:73]
	s_cbranch_execz .LBB0_1185
	s_load_dwordx2 s[6:7], s[0:1], 0x158
	s_load_dword s8, s[0:1], 0x490
	s_getreg_b32 s9, hwreg(HW_REG_XCC_ID, 0, 4)
	v_mov_b32_e32 v0, 0
	v_mov_b32_e32 v1, 1
	s_lshl_b32 s9, s9, 2
	v_mov_b32_e32 v3, s9
	s_waitcnt lgkmcnt(0)
	global_atomic_add v2, v3, v1, s[6:7] offset:160 sc0
	global_load_dword v3, v0, s[6:7] offset:140 sc1
	s_lshr_b32 s10, s8, 3
	s_mul_i32 s10, s10, 6
	s_waitcnt vmcnt(0)
	v_cmp_ne_u32_e32 vcc, 0, v3
	s_cbranch_vccnz .Lgs8_flat
	v_add_u32_e32 v2, 1, v2
	v_cmp_ne_u32_e32 vcc, s10, v2
	s_cbranch_vccnz .Lgs8_wait
	buffer_wbl2 sc1
	s_waitcnt vmcnt(0)
	global_atomic_add v0, v1, s[6:7] offset:136
.Lgs8_wait:
	s_movk_i32 s10, 48
	s_movk_i32 s11, 0x4000

; #define RUNPH(k, call) for (int rep_ = 0; rep_ < (((REPMASK) >> (k)) & 1) + 1; ++rep_) { call; grid.sync(); }
; __global__ void __launch_bounds__(NTH, 2) mega_kernel(Params p) {
;     ...
;   RUNPH(8, phase8(p))
.Lgs8_flat:
	buffer_wbl2 sc1
	s_waitcnt vmcnt(0)
	global_atomic_add v0, v1, s[6:7] offset:128
	s_mul_i32 s8, s8, 8

; __global__ void __launch_bounds__(NTH, 2) mega_kernel(Params p) {
;     ...
;   grid.sync();
.LBB0_1372:
	s_waitcnt vmcnt(0) lgkmcnt(0)
	s_barrier
	s_and_saveexec_b64 s[2:3], s[72:73]
	s_cbranch_execz .LBB0_1382
	s_load_dwordx2 s[6:7], s[0:1], 0x158
	s_load_dword s8, s[0:1], 0x490
	s_getreg_b32 s9, hwreg(HW_REG_XCC_ID, 0, 4)
	v_mov_b32_e32 v0, 0
	v_mov_b32_e32 v1, 1
	s_lshl_b32 s9, s9, 2
	v_mov_b32_e32 v3, s9
	s_waitcnt lgkmcnt(0)
	global_atomic_add v2, v3, v1, s[6:7] offset:160 sc0
	global_load_dword v3, v0, s[6:7] offset:140 sc1
	s_lshr_b32 s10, s8, 3
	s_mul_i32 s10, s10, 7
	s_waitcnt vmcnt(0)
	v_cmp_ne_u32_e32 vcc, 0, v3
	s_cbranch_vccnz .Lgs9_flat
	v_add_u32_e32 v2, 1, v2
	v_cmp_ne_u32_e32 vcc, s10, v2
	s_cbranch_vccnz .Lgs9_wait
	buffer_wbl2 sc1
	s_waitcnt vmcnt(0)
	global_atomic_add v0, v1, s[6:7] offset:136
.Lgs9_wait:
	s_movk_i32 s10, 56
	s_movk_i32 s11, 0x4000

; __global__ void __launch_bounds__(NTH, 2) mega_kernel(Params p) {
;     ...
;   grid.sync();
.Lgs9_flat:
	buffer_wbl2 sc1
	s_waitcnt vmcnt(0)
	global_atomic_add v0, v1, s[6:7] offset:128
	s_mul_i32 s8, s8, 9
